# final RMSNorm pass hand-written: gains hoisted into 64 VGPRs, next row's loads issued before the current row's stores, one counted vmcnt per row
# speedup vs baseline: 1.0124x; 1.0124x over previous
; __device__ __forceinline__ void final_pass(const Params& p, int G) {
;     ...
;     const int lane = threadIdx.x & 63, gw = blockIdx.x * NWAVES + (threadIdx.x >> 6), NGW = G * NWAVES;
;     for (int m = gw; m < T; m += NGW) {
;         const float rstd = __builtin_amdgcn_rsqf(ctl[CF_SS3 + m] * (1.f / DM) + EPS);
;         const u32x4* hr = (const u32x4*)(h2b + (size_t)m * DM) + lane; f32x4* xr = (f32x4*)(p.out + (size_t)m * DM) + 2 * lane; const f32x4* gr = (const f32x4*)p.fin_g + 2 * lane;
;         u32x4 hv[8];
; #pragma unroll
;         for (int j = 0; j < 8; ++j) hv[j] = hr[64 * j];
; #pragma unroll
;         for (int j = 0; j < 8; ++j) { const u32x4 w = hv[j]; const f32x4 g0 = gr[128 * j], g1 = gr[128 * j + 1];
.LBB0_1051:
	s_cmp_lt_i32 s40, 9
	s_cselect_b64 s[0:1], -1, 0
	s_and_b64 s[0:1], s[0:1], s[2:3]
	s_andn2_b64 vcc, exec, s[0:1]
	s_cbranch_vccnz .LBB0_1055
	v_lshrrev_b32_e32 v0, 6, v208
	v_lshl_add_u32 v12, s46, 3, v0
	s_movk_i32 s0, 0x4000
	v_cmp_gt_i32_e32 vcc, s0, v12
	s_and_saveexec_b64 s[0:1], vcc
	s_cbranch_execz .LBB0_1055
	v_and_b32_e32 v4, 63, v208
	v_lshlrev_b32_e32 v0, 5, v4
	v_mov_b32_e32 v1, 0
	v_lshl_add_u64 v[14:15], s[82:83], 0, v[0:1]
	s_mov_b64 s[2:3], 0x1000
	v_lshl_add_u64 v[16:17], v[14:15], 0, s[2:3]
	s_mov_b64 s[2:3], 0x1800
	v_lshl_add_u64 v[18:19], v[14:15], 0, s[2:3]
	s_mov_b64 s[2:3], 0x2000
	v_lshl_add_u64 v[20:21], v[14:15], 0, s[2:3]
	s_mov_b64 s[2:3], 0x2800
	v_ashrrev_i32_e32 v13, 31, v12
	s_waitcnt lgkmcnt(0)
	v_mov_b64_e32 v[2:3], 0x40000
	s_lshl_b32 s0, s90, 3
	v_lshl_add_u64 v[22:23], v[14:15], 0, s[2:3]
	s_mov_b64 s[2:3], 0x3000
	v_lshl_add_u64 v[28:29], v[12:13], 2, v[2:3]
	v_lshlrev_b64 v[2:3], 14, v[12:13]
	v_lshl_add_u64 v[24:25], v[14:15], 0, s[2:3]
	s_mov_b64 s[2:3], 0x3800
	s_ashr_i32 s1, s0, 31
	v_lshlrev_b64 v[30:31], 13, v[12:13]
	v_or_b32_e32 v2, v2, v0
	v_lshl_add_u64 v[26:27], v[14:15], 0, s[2:3]
	s_lshl_b64 s[2:3], s[0:1], 2
	v_lshl_or_b32 v30, v4, 4, v30
	s_lshl_b64 s[4:5], s[0:1], 13
	v_lshl_add_u64 v[32:33], s[84:85], 0, v[2:3]
	s_lshl_b64 s[6:7], s[0:1], 14
	s_mov_b64 s[8:9], 0
	v_mov_b32_e32 v13, 0x358637bd
	s_mov_b32 s1, 0x35fa1000
	s_movk_i32 s10, 0x1000
	s_movk_i32 s11, 0x2000
	s_movk_i32 s12, 0x3000
	s_movk_i32 s13, 0x3fff
	global_load_dwordx4 v[68:71], v[14:15], off
	global_load_dwordx4 v[72:75], v[14:15], off offset:16
	global_load_dwordx4 v[76:79], v[14:15], off offset:2048
	global_load_dwordx4 v[80:83], v[14:15], off offset:2064
	global_load_dwordx4 v[84:87], v[16:17], off
	global_load_dwordx4 v[88:91], v[16:17], off offset:16
	global_load_dwordx4 v[92:95], v[18:19], off
	global_load_dwordx4 v[96:99], v[18:19], off offset:16
	global_load_dwordx4 v[100:103], v[20:21], off
	global_load_dwordx4 v[104:107], v[20:21], off offset:16
	global_load_dwordx4 v[108:111], v[22:23], off
	global_load_dwordx4 v[112:115], v[22:23], off offset:16
	global_load_dwordx4 v[116:119], v[24:25], off
	global_load_dwordx4 v[120:123], v[24:25], off offset:16
	global_load_dwordx4 v[124:127], v[26:27], off
	global_load_dwordx4 v[128:131], v[26:27], off offset:16
	s_mov_b64 s[16:17], 0x1000
	s_mov_b64 s[18:19], 0x2000
	s_mov_b64 s[20:21], 0x3000
	v_readfirstlane_b32 s14, v12
	v_lshl_add_u64 v[0:1], s[86:87], 0, v[28:29]
	global_load_dword v196, v[0:1], off
	v_lshl_add_u64 v[2:3], s[86:87], 0, v[30:31]
	v_add_co_u32_e32 v34, vcc, 0x35fa0000, v2
	s_nop 1
	v_addc_co_u32_e32 v35, vcc, 0, v3, vcc
	v_add_co_u32_e32 v64, vcc, s1, v2
	s_nop 1
	v_addc_co_u32_e32 v65, vcc, 0, v3, vcc
	global_load_dwordx4 v[132:135], v[34:35], off
	global_load_dwordx4 v[136:139], v[34:35], off offset:1024
	global_load_dwordx4 v[140:143], v[34:35], off offset:2048
	global_load_dwordx4 v[144:147], v[34:35], off offset:3072
	global_load_dwordx4 v[148:151], v[64:65], off
	global_load_dwordx4 v[152:155], v[64:65], off offset:1024
	global_load_dwordx4 v[156:159], v[64:65], off offset:2048
	global_load_dwordx4 v[160:163], v[64:65], off offset:3072
	v_lshl_add_u64 v[28:29], v[28:29], 0, s[2:3]
	v_lshl_add_u64 v[30:31], v[30:31], 0, s[4:5]
.Lfin_loop:
	s_add_i32 s15, s14, s0
	s_cmp_lt_i32 s15, 0x4000
	s_cbranch_scc0 .Lfin_last_a
	v_lshl_add_u64 v[0:1], s[86:87], 0, v[28:29]
	global_load_dword v197, v[0:1], off
	v_lshl_add_u64 v[2:3], s[86:87], 0, v[30:31]
	v_add_co_u32_e32 v34, vcc, 0x35fa0000, v2
	s_nop 1
	v_addc_co_u32_e32 v35, vcc, 0, v3, vcc
	v_add_co_u32_e32 v64, vcc, s1, v2
	s_nop 1
	v_addc_co_u32_e32 v65, vcc, 0, v3, vcc
	global_load_dwordx4 v[164:167], v[34:35], off
	global_load_dwordx4 v[168:171], v[34:35], off offset:1024
	global_load_dwordx4 v[172:175], v[34:35], off offset:2048
	global_load_dwordx4 v[176:179], v[34:35], off offset:3072
	global_load_dwordx4 v[180:183], v[64:65], off
	global_load_dwordx4 v[184:187], v[64:65], off offset:1024
	global_load_dwordx4 v[188:191], v[64:65], off offset:2048
	global_load_dwordx4 v[192:195], v[64:65], off offset:3072
	v_lshl_add_u64 v[28:29], v[28:29], 0, s[2:3]
	v_lshl_add_u64 v[30:31], v[30:31], 0, s[4:5]
	s_waitcnt vmcnt(9)
; __device__ __forceinline__ void final_pass(const Params& p, int G) {
;     ...
;         for (int j = 0; j < 8; ++j) { const u32x4 w = hv[j]; const f32x4 g0 = gr[128 * j], g1 = gr[128 * j + 1];
;             const f32x4 v0 = (f32x4){__builtin_bit_cast(float, w.x << 16), __builtin_bit_cast(float, w.x & 0xffff0000u), __builtin_bit_cast(float, w.y << 16), __builtin_bit_cast(float, w.y & 0xffff0000u)};
;             const f32x4 v1 = (f32x4){__builtin_bit_cast(float, w.z << 16), __builtin_bit_cast(float, w.z & 0xffff0000u), __builtin_bit_cast(float, w.w << 16), __builtin_bit_cast(float, w.w & 0xffff0000u)};
;             __builtin_nontemporal_store(v0 * rstd * g0, xr + 128 * j); __builtin_nontemporal_store(v1 * rstd * g1, xr + 128 * j + 1); }
	v_fmamk_f32 v36, v196, 0x39800000, v13
	v_rsq_f32_e32 v36, v36
	v_lshl_add_u64 v[38:39], v[32:33], 0, s[16:17]
	v_lshl_add_u64 v[40:41], v[32:33], 0, s[18:19]
	v_lshl_add_u64 v[42:43], v[32:33], 0, s[20:21]
	v_lshlrev_b32_e32 v216, 16, v132
	v_and_b32_e32 v217, 0xffff0000, v132
	v_lshlrev_b32_e32 v218, 16, v133
	v_and_b32_e32 v219, 0xffff0000, v133
	v_lshlrev_b32_e32 v220, 16, v134
	v_and_b32_e32 v221, 0xffff0000, v134
	v_lshlrev_b32_e32 v222, 16, v135
	v_and_b32_e32 v223, 0xffff0000, v135
	v_pk_mul_f32 v[216:217], v[36:37], v[216:217] op_sel_hi:[0,1]
	v_pk_mul_f32 v[218:219], v[36:37], v[218:219] op_sel_hi:[0,1]
	v_pk_mul_f32 v[220:221], v[36:37], v[220:221] op_sel_hi:[0,1]
	v_pk_mul_f32 v[222:223], v[36:37], v[222:223] op_sel_hi:[0,1]
	v_pk_mul_f32 v[216:217], v[216:217], v[68:69]
	v_pk_mul_f32 v[218:219], v[218:219], v[70:71]
	v_pk_mul_f32 v[220:221], v[220:221], v[72:73]
	v_pk_mul_f32 v[222:223], v[222:223], v[74:75]
	global_store_dwordx4 v[32:33], v[216:219], off nt
	global_store_dwordx4 v[32:33], v[220:223], off offset:16 nt
	v_lshlrev_b32_e32 v224, 16, v136
	v_and_b32_e32 v225, 0xffff0000, v136
	v_lshlrev_b32_e32 v226, 16, v137
	v_and_b32_e32 v227, 0xffff0000, v137
	v_lshlrev_b32_e32 v228, 16, v138
	v_and_b32_e32 v229, 0xffff0000, v138
	v_lshlrev_b32_e32 v230, 16, v139
	v_and_b32_e32 v231, 0xffff0000, v139
	v_pk_mul_f32 v[224:225], v[36:37], v[224:225] op_sel_hi:[0,1]
	v_pk_mul_f32 v[226:227], v[36:37], v[226:227] op_sel_hi:[0,1]
	v_pk_mul_f32 v[228:229], v[36:37], v[228:229] op_sel_hi:[0,1]
	v_pk_mul_f32 v[230:231], v[36:37], v[230:231] op_sel_hi:[0,1]
	v_pk_mul_f32 v[224:225], v[224:225], v[76:77]
	v_pk_mul_f32 v[226:227], v[226:227], v[78:79]
	v_pk_mul_f32 v[228:229], v[228:229], v[80:81]
	v_pk_mul_f32 v[230:231], v[230:231], v[82:83]
	global_store_dwordx4 v[32:33], v[224:227], off offset:2048 nt
	global_store_dwordx4 v[32:33], v[228:231], off offset:2064 nt
	v_lshlrev_b32_e32 v216, 16, v140
	v_and_b32_e32 v217, 0xffff0000, v140
	v_lshlrev_b32_e32 v218, 16, v141
	v_and_b32_e32 v219, 0xffff0000, v141
	v_lshlrev_b32_e32 v220, 16, v142
	v_and_b32_e32 v221, 0xffff0000, v142
	v_lshlrev_b32_e32 v222, 16, v143
	v_and_b32_e32 v223, 0xffff0000, v143
	v_pk_mul_f32 v[216:217], v[36:37], v[216:217] op_sel_hi:[0,1]
	v_pk_mul_f32 v[218:219], v[36:37], v[218:219] op_sel_hi:[0,1]
	v_pk_mul_f32 v[220:221], v[36:37], v[220:221] op_sel_hi:[0,1]
	v_pk_mul_f32 v[222:223], v[36:37], v[222:223] op_sel_hi:[0,1]
	v_pk_mul_f32 v[216:217], v[216:217], v[84:85]
	v_pk_mul_f32 v[218:219], v[218:219], v[86:87]
	v_pk_mul_f32 v[220:221], v[220:221], v[88:89]
	v_pk_mul_f32 v[222:223], v[222:223], v[90:91]
	global_store_dwordx4 v[38:39], v[216:219], off nt
	global_store_dwordx4 v[38:39], v[220:223], off offset:16 nt
	v_lshlrev_b32_e32 v224, 16, v144
	v_and_b32_e32 v225, 0xffff0000, v144
	v_lshlrev_b32_e32 v226, 16, v145
	v_and_b32_e32 v227, 0xffff0000, v145
	v_lshlrev_b32_e32 v228, 16, v146
	v_and_b32_e32 v229, 0xffff0000, v146
	v_lshlrev_b32_e32 v230, 16, v147
	v_and_b32_e32 v231, 0xffff0000, v147
	v_pk_mul_f32 v[224:225], v[36:37], v[224:225] op_sel_hi:[0,1]
	v_pk_mul_f32 v[226:227], v[36:37], v[226:227] op_sel_hi:[0,1]
	v_pk_mul_f32 v[228:229], v[36:37], v[228:229] op_sel_hi:[0,1]
	v_pk_mul_f32 v[230:231], v[36:37], v[230:231] op_sel_hi:[0,1]
	v_pk_mul_f32 v[224:225], v[224:225], v[92:93]
	v_pk_mul_f32 v[226:227], v[226:227], v[94:95]
	v_pk_mul_f32 v[228:229], v[228:229], v[96:97]
	v_pk_mul_f32 v[230:231], v[230:231], v[98:99]
	global_store_dwordx4 v[38:39], v[224:227], off offset:2048 nt
	global_store_dwordx4 v[38:39], v[228:231], off offset:2064 nt
	v_lshlrev_b32_e32 v216, 16, v148
	v_and_b32_e32 v217, 0xffff0000, v148
	v_lshlrev_b32_e32 v218, 16, v149
	v_and_b32_e32 v219, 0xffff0000, v149
	v_lshlrev_b32_e32 v220, 16, v150
	v_and_b32_e32 v221, 0xffff0000, v150
	v_lshlrev_b32_e32 v222, 16, v151
	v_and_b32_e32 v223, 0xffff0000, v151
	v_pk_mul_f32 v[216:217], v[36:37], v[216:217] op_sel_hi:[0,1]
	v_pk_mul_f32 v[218:219], v[36:37], v[218:219] op_sel_hi:[0,1]
	v_pk_mul_f32 v[220:221], v[36:37], v[220:221] op_sel_hi:[0,1]
	v_pk_mul_f32 v[222:223], v[36:37], v[222:223] op_sel_hi:[0,1]
	v_pk_mul_f32 v[216:217], v[216:217], v[100:101]
	v_pk_mul_f32 v[218:219], v[218:219], v[102:103]
	v_pk_mul_f32 v[220:221], v[220:221], v[104:105]
	v_pk_mul_f32 v[222:223], v[222:223], v[106:107]
	global_store_dwordx4 v[40:41], v[216:219], off nt
	global_store_dwordx4 v[40:41], v[220:223], off offset:16 nt
	v_lshlrev_b32_e32 v224, 16, v152
	v_and_b32_e32 v225, 0xffff0000, v152
	v_lshlrev_b32_e32 v226, 16, v153
	v_and_b32_e32 v227, 0xffff0000, v153
	v_lshlrev_b32_e32 v228, 16, v154
	v_and_b32_e32 v229, 0xffff0000, v154
	v_lshlrev_b32_e32 v230, 16, v155
	v_and_b32_e32 v231, 0xffff0000, v155
	v_pk_mul_f32 v[224:225], v[36:37], v[224:225] op_sel_hi:[0,1]
	v_pk_mul_f32 v[226:227], v[36:37], v[226:227] op_sel_hi:[0,1]
	v_pk_mul_f32 v[228:229], v[36:37], v[228:229] op_sel_hi:[0,1]
	v_pk_mul_f32 v[230:231], v[36:37], v[230:231] op_sel_hi:[0,1]
	v_pk_mul_f32 v[224:225], v[224:225], v[108:109]
	v_pk_mul_f32 v[226:227], v[226:227], v[110:111]
	v_pk_mul_f32 v[228:229], v[228:229], v[112:113]
	v_pk_mul_f32 v[230:231], v[230:231], v[114:115]
	global_store_dwordx4 v[40:41], v[224:227], off offset:2048 nt
	global_store_dwordx4 v[40:41], v[228:231], off offset:2064 nt
	v_lshlrev_b32_e32 v216, 16, v156
	v_and_b32_e32 v217, 0xffff0000, v156
	v_lshlrev_b32_e32 v218, 16, v157
	v_and_b32_e32 v219, 0xffff0000, v157
	v_lshlrev_b32_e32 v220, 16, v158
	v_and_b32_e32 v221, 0xffff0000, v158
	v_lshlrev_b32_e32 v222, 16, v159
	v_and_b32_e32 v223, 0xffff0000, v159
	v_pk_mul_f32 v[216:217], v[36:37], v[216:217] op_sel_hi:[0,1]
; __device__ __forceinline__ void final_pass(const Params& p, int G) {
;     ...
;         for (int j = 0; j < 8; ++j) hv[j] = hr[64 * j];
; #pragma unroll
;         for (int j = 0; j < 8; ++j) { const u32x4 w = hv[j]; const f32x4 g0 = gr[128 * j], g1 = gr[128 * j + 1];
;             const f32x4 v0 = (f32x4){__builtin_bit_cast(float, w.x << 16), __builtin_bit_cast(float, w.x & 0xffff0000u), __builtin_bit_cast(float, w.y << 16), __builtin_bit_cast(float, w.y & 0xffff0000u)};
;             const f32x4 v1 = (f32x4){__builtin_bit_cast(float, w.z << 16), __builtin_bit_cast(float, w.z & 0xffff0000u), __builtin_bit_cast(float, w.w << 16), __builtin_bit_cast(float, w.w & 0xffff0000u)};
;             __builtin_nontemporal_store(v0 * rstd * g0, xr + 128 * j); __builtin_nontemporal_store(v1 * rstd * g1, xr + 128 * j + 1); }
	v_pk_mul_f32 v[218:219], v[36:37], v[218:219] op_sel_hi:[0,1]
	v_pk_mul_f32 v[220:221], v[36:37], v[220:221] op_sel_hi:[0,1]
	v_pk_mul_f32 v[222:223], v[36:37], v[222:223] op_sel_hi:[0,1]
	v_pk_mul_f32 v[216:217], v[216:217], v[116:117]
	v_pk_mul_f32 v[218:219], v[218:219], v[118:119]
	v_pk_mul_f32 v[220:221], v[220:221], v[120:121]
	v_pk_mul_f32 v[222:223], v[222:223], v[122:123]
	global_store_dwordx4 v[42:43], v[216:219], off nt
	global_store_dwordx4 v[42:43], v[220:223], off offset:16 nt
	v_lshlrev_b32_e32 v224, 16, v160
	v_and_b32_e32 v225, 0xffff0000, v160
	v_lshlrev_b32_e32 v226, 16, v161
	v_and_b32_e32 v227, 0xffff0000, v161
	v_lshlrev_b32_e32 v228, 16, v162
	v_and_b32_e32 v229, 0xffff0000, v162
	v_lshlrev_b32_e32 v230, 16, v163
	v_and_b32_e32 v231, 0xffff0000, v163
	v_pk_mul_f32 v[224:225], v[36:37], v[224:225] op_sel_hi:[0,1]
	v_pk_mul_f32 v[226:227], v[36:37], v[226:227] op_sel_hi:[0,1]
	v_pk_mul_f32 v[228:229], v[36:37], v[228:229] op_sel_hi:[0,1]
	v_pk_mul_f32 v[230:231], v[36:37], v[230:231] op_sel_hi:[0,1]
	v_pk_mul_f32 v[224:225], v[224:225], v[124:125]
	v_pk_mul_f32 v[226:227], v[226:227], v[126:127]
	v_pk_mul_f32 v[228:229], v[228:229], v[128:129]
	v_pk_mul_f32 v[230:231], v[230:231], v[130:131]
	global_store_dwordx4 v[42:43], v[224:227], off offset:2048 nt
	global_store_dwordx4 v[42:43], v[228:231], off offset:2064 nt
	v_lshl_add_u64 v[32:33], v[32:33], 0, s[6:7]
	s_mov_b32 s14, s15
	s_add_i32 s15, s14, s0
	s_cmp_lt_i32 s15, 0x4000
	s_cbranch_scc0 .Lfin_last_b
	v_lshl_add_u64 v[0:1], s[86:87], 0, v[28:29]
	global_load_dword v196, v[0:1], off
	v_lshl_add_u64 v[2:3], s[86:87], 0, v[30:31]
	v_add_co_u32_e32 v34, vcc, 0x35fa0000, v2
	s_nop 1
	v_addc_co_u32_e32 v35, vcc, 0, v3, vcc
	v_add_co_u32_e32 v64, vcc, s1, v2
	s_nop 1
	v_addc_co_u32_e32 v65, vcc, 0, v3, vcc
	global_load_dwordx4 v[132:135], v[34:35], off
	global_load_dwordx4 v[136:139], v[34:35], off offset:1024
	global_load_dwordx4 v[140:143], v[34:35], off offset:2048
	global_load_dwordx4 v[144:147], v[34:35], off offset:3072
	global_load_dwordx4 v[148:151], v[64:65], off
	global_load_dwordx4 v[152:155], v[64:65], off offset:1024
	global_load_dwordx4 v[156:159], v[64:65], off offset:2048
	global_load_dwordx4 v[160:163], v[64:65], off offset:3072
	v_lshl_add_u64 v[28:29], v[28:29], 0, s[2:3]
	v_lshl_add_u64 v[30:31], v[30:31], 0, s[4:5]
	s_waitcnt vmcnt(9)
	v_fmamk_f32 v36, v197, 0x39800000, v13
	v_rsq_f32_e32 v36, v36
	v_lshl_add_u64 v[38:39], v[32:33], 0, s[16:17]
	v_lshl_add_u64 v[40:41], v[32:33], 0, s[18:19]
	v_lshl_add_u64 v[42:43], v[32:33], 0, s[20:21]
	v_lshlrev_b32_e32 v216, 16, v164
	v_and_b32_e32 v217, 0xffff0000, v164
	v_lshlrev_b32_e32 v218, 16, v165
	v_and_b32_e32 v219, 0xffff0000, v165
	v_lshlrev_b32_e32 v220, 16, v166
	v_and_b32_e32 v221, 0xffff0000, v166
	v_lshlrev_b32_e32 v222, 16, v167
	v_and_b32_e32 v223, 0xffff0000, v167
	v_pk_mul_f32 v[216:217], v[36:37], v[216:217] op_sel_hi:[0,1]
	v_pk_mul_f32 v[218:219], v[36:37], v[218:219] op_sel_hi:[0,1]
	v_pk_mul_f32 v[220:221], v[36:37], v[220:221] op_sel_hi:[0,1]
	v_pk_mul_f32 v[222:223], v[36:37], v[222:223] op_sel_hi:[0,1]
	v_pk_mul_f32 v[216:217], v[216:217], v[68:69]
	v_pk_mul_f32 v[218:219], v[218:219], v[70:71]
	v_pk_mul_f32 v[220:221], v[220:221], v[72:73]
	v_pk_mul_f32 v[222:223], v[222:223], v[74:75]
	global_store_dwordx4 v[32:33], v[216:219], off nt
	global_store_dwordx4 v[32:33], v[220:223], off offset:16 nt
	v_lshlrev_b32_e32 v224, 16, v168
	v_and_b32_e32 v225, 0xffff0000, v168
	v_lshlrev_b32_e32 v226, 16, v169
	v_and_b32_e32 v227, 0xffff0000, v169
	v_lshlrev_b32_e32 v228, 16, v170
	v_and_b32_e32 v229, 0xffff0000, v170
	v_lshlrev_b32_e32 v230, 16, v171
	v_and_b32_e32 v231, 0xffff0000, v171
	v_pk_mul_f32 v[224:225], v[36:37], v[224:225] op_sel_hi:[0,1]
	v_pk_mul_f32 v[226:227], v[36:37], v[226:227] op_sel_hi:[0,1]
	v_pk_mul_f32 v[228:229], v[36:37], v[228:229] op_sel_hi:[0,1]
	v_pk_mul_f32 v[230:231], v[36:37], v[230:231] op_sel_hi:[0,1]
	v_pk_mul_f32 v[224:225], v[224:225], v[76:77]
	v_pk_mul_f32 v[226:227], v[226:227], v[78:79]
	v_pk_mul_f32 v[228:229], v[228:229], v[80:81]
	v_pk_mul_f32 v[230:231], v[230:231], v[82:83]
	global_store_dwordx4 v[32:33], v[224:227], off offset:2048 nt
	global_store_dwordx4 v[32:33], v[228:231], off offset:2064 nt
	v_lshlrev_b32_e32 v216, 16, v172
	v_and_b32_e32 v217, 0xffff0000, v172
	v_lshlrev_b32_e32 v218, 16, v173
	v_and_b32_e32 v219, 0xffff0000, v173
	v_lshlrev_b32_e32 v220, 16, v174
	v_and_b32_e32 v221, 0xffff0000, v174
	v_lshlrev_b32_e32 v222, 16, v175
	v_and_b32_e32 v223, 0xffff0000, v175
	v_pk_mul_f32 v[216:217], v[36:37], v[216:217] op_sel_hi:[0,1]
	v_pk_mul_f32 v[218:219], v[36:37], v[218:219] op_sel_hi:[0,1]
	v_pk_mul_f32 v[220:221], v[36:37], v[220:221] op_sel_hi:[0,1]
	v_pk_mul_f32 v[222:223], v[36:37], v[222:223] op_sel_hi:[0,1]
	v_pk_mul_f32 v[216:217], v[216:217], v[84:85]
	v_pk_mul_f32 v[218:219], v[218:219], v[86:87]
	v_pk_mul_f32 v[220:221], v[220:221], v[88:89]
	v_pk_mul_f32 v[222:223], v[222:223], v[90:91]
	global_store_dwordx4 v[38:39], v[216:219], off nt
	global_store_dwordx4 v[38:39], v[220:223], off offset:16 nt
	v_lshlrev_b32_e32 v224, 16, v176
	v_and_b32_e32 v225, 0xffff0000, v176
	v_lshlrev_b32_e32 v226, 16, v177
	v_and_b32_e32 v227, 0xffff0000, v177
	v_lshlrev_b32_e32 v228, 16, v178
	v_and_b32_e32 v229, 0xffff0000, v178
	v_lshlrev_b32_e32 v230, 16, v179
	v_and_b32_e32 v231, 0xffff0000, v179
	v_pk_mul_f32 v[224:225], v[36:37], v[224:225] op_sel_hi:[0,1]
	v_pk_mul_f32 v[226:227], v[36:37], v[226:227] op_sel_hi:[0,1]
	v_pk_mul_f32 v[228:229], v[36:37], v[228:229] op_sel_hi:[0,1]
	v_pk_mul_f32 v[230:231], v[36:37], v[230:231] op_sel_hi:[0,1]
; __device__ __forceinline__ void final_pass(const Params& p, int G) {
;     ...
;         for (int j = 0; j < 8; ++j) hv[j] = hr[64 * j];
; #pragma unroll
;         for (int j = 0; j < 8; ++j) { const u32x4 w = hv[j]; const f32x4 g0 = gr[128 * j], g1 = gr[128 * j + 1];
;             const f32x4 v0 = (f32x4){__builtin_bit_cast(float, w.x << 16), __builtin_bit_cast(float, w.x & 0xffff0000u), __builtin_bit_cast(float, w.y << 16), __builtin_bit_cast(float, w.y & 0xffff0000u)};
;             const f32x4 v1 = (f32x4){__builtin_bit_cast(float, w.z << 16), __builtin_bit_cast(float, w.z & 0xffff0000u), __builtin_bit_cast(float, w.w << 16), __builtin_bit_cast(float, w.w & 0xffff0000u)};
;             __builtin_nontemporal_store(v0 * rstd * g0, xr + 128 * j); __builtin_nontemporal_store(v1 * rstd * g1, xr + 128 * j + 1); }
	v_pk_mul_f32 v[224:225], v[224:225], v[92:93]
	v_pk_mul_f32 v[226:227], v[226:227], v[94:95]
	v_pk_mul_f32 v[228:229], v[228:229], v[96:97]
	v_pk_mul_f32 v[230:231], v[230:231], v[98:99]
	global_store_dwordx4 v[38:39], v[224:227], off offset:2048 nt
	global_store_dwordx4 v[38:39], v[228:231], off offset:2064 nt
	v_lshlrev_b32_e32 v216, 16, v180
	v_and_b32_e32 v217, 0xffff0000, v180
	v_lshlrev_b32_e32 v218, 16, v181
	v_and_b32_e32 v219, 0xffff0000, v181
	v_lshlrev_b32_e32 v220, 16, v182
	v_and_b32_e32 v221, 0xffff0000, v182
	v_lshlrev_b32_e32 v222, 16, v183
	v_and_b32_e32 v223, 0xffff0000, v183
	v_pk_mul_f32 v[216:217], v[36:37], v[216:217] op_sel_hi:[0,1]
	v_pk_mul_f32 v[218:219], v[36:37], v[218:219] op_sel_hi:[0,1]
	v_pk_mul_f32 v[220:221], v[36:37], v[220:221] op_sel_hi:[0,1]
	v_pk_mul_f32 v[222:223], v[36:37], v[222:223] op_sel_hi:[0,1]
	v_pk_mul_f32 v[216:217], v[216:217], v[100:101]
	v_pk_mul_f32 v[218:219], v[218:219], v[102:103]
	v_pk_mul_f32 v[220:221], v[220:221], v[104:105]
	v_pk_mul_f32 v[222:223], v[222:223], v[106:107]
	global_store_dwordx4 v[40:41], v[216:219], off nt
	global_store_dwordx4 v[40:41], v[220:223], off offset:16 nt
	v_lshlrev_b32_e32 v224, 16, v184
	v_and_b32_e32 v225, 0xffff0000, v184
	v_lshlrev_b32_e32 v226, 16, v185
	v_and_b32_e32 v227, 0xffff0000, v185
	v_lshlrev_b32_e32 v228, 16, v186
	v_and_b32_e32 v229, 0xffff0000, v186
	v_lshlrev_b32_e32 v230, 16, v187
	v_and_b32_e32 v231, 0xffff0000, v187
	v_pk_mul_f32 v[224:225], v[36:37], v[224:225] op_sel_hi:[0,1]
	v_pk_mul_f32 v[226:227], v[36:37], v[226:227] op_sel_hi:[0,1]
	v_pk_mul_f32 v[228:229], v[36:37], v[228:229] op_sel_hi:[0,1]
	v_pk_mul_f32 v[230:231], v[36:37], v[230:231] op_sel_hi:[0,1]
	v_pk_mul_f32 v[224:225], v[224:225], v[108:109]
	v_pk_mul_f32 v[226:227], v[226:227], v[110:111]
	v_pk_mul_f32 v[228:229], v[228:229], v[112:113]
	v_pk_mul_f32 v[230:231], v[230:231], v[114:115]
	global_store_dwordx4 v[40:41], v[224:227], off offset:2048 nt
	global_store_dwordx4 v[40:41], v[228:231], off offset:2064 nt
	v_lshlrev_b32_e32 v216, 16, v188
	v_and_b32_e32 v217, 0xffff0000, v188
	v_lshlrev_b32_e32 v218, 16, v189
	v_and_b32_e32 v219, 0xffff0000, v189
	v_lshlrev_b32_e32 v220, 16, v190
	v_and_b32_e32 v221, 0xffff0000, v190
	v_lshlrev_b32_e32 v222, 16, v191
	v_and_b32_e32 v223, 0xffff0000, v191
	v_pk_mul_f32 v[216:217], v[36:37], v[216:217] op_sel_hi:[0,1]
	v_pk_mul_f32 v[218:219], v[36:37], v[218:219] op_sel_hi:[0,1]
	v_pk_mul_f32 v[220:221], v[36:37], v[220:221] op_sel_hi:[0,1]
	v_pk_mul_f32 v[222:223], v[36:37], v[222:223] op_sel_hi:[0,1]
	v_pk_mul_f32 v[216:217], v[216:217], v[116:117]
	v_pk_mul_f32 v[218:219], v[218:219], v[118:119]
	v_pk_mul_f32 v[220:221], v[220:221], v[120:121]
	v_pk_mul_f32 v[222:223], v[222:223], v[122:123]
	global_store_dwordx4 v[42:43], v[216:219], off nt
	global_store_dwordx4 v[42:43], v[220:223], off offset:16 nt
	v_lshlrev_b32_e32 v224, 16, v192
	v_and_b32_e32 v225, 0xffff0000, v192
	v_lshlrev_b32_e32 v226, 16, v193
	v_and_b32_e32 v227, 0xffff0000, v193
	v_lshlrev_b32_e32 v228, 16, v194
	v_and_b32_e32 v229, 0xffff0000, v194
	v_lshlrev_b32_e32 v230, 16, v195
	v_and_b32_e32 v231, 0xffff0000, v195
	v_pk_mul_f32 v[224:225], v[36:37], v[224:225] op_sel_hi:[0,1]
	v_pk_mul_f32 v[226:227], v[36:37], v[226:227] op_sel_hi:[0,1]
	v_pk_mul_f32 v[228:229], v[36:37], v[228:229] op_sel_hi:[0,1]
	v_pk_mul_f32 v[230:231], v[36:37], v[230:231] op_sel_hi:[0,1]
	v_pk_mul_f32 v[224:225], v[224:225], v[124:125]
	v_pk_mul_f32 v[226:227], v[226:227], v[126:127]
	v_pk_mul_f32 v[228:229], v[228:229], v[128:129]
	v_pk_mul_f32 v[230:231], v[230:231], v[130:131]
	global_store_dwordx4 v[42:43], v[224:227], off offset:2048 nt
	global_store_dwordx4 v[42:43], v[228:231], off offset:2064 nt
	v_lshl_add_u64 v[32:33], v[32:33], 0, s[6:7]
	s_mov_b32 s14, s15
	s_branch .Lfin_loop
.Lfin_last_a:
	s_waitcnt vmcnt(0)
	v_fmamk_f32 v36, v196, 0x39800000, v13
	v_rsq_f32_e32 v36, v36
	v_lshl_add_u64 v[38:39], v[32:33], 0, s[16:17]
	v_lshl_add_u64 v[40:41], v[32:33], 0, s[18:19]
	v_lshl_add_u64 v[42:43], v[32:33], 0, s[20:21]
	v_lshlrev_b32_e32 v216, 16, v132
	v_and_b32_e32 v217, 0xffff0000, v132
	v_lshlrev_b32_e32 v218, 16, v133
	v_and_b32_e32 v219, 0xffff0000, v133
	v_lshlrev_b32_e32 v220, 16, v134
	v_and_b32_e32 v221, 0xffff0000, v134
	v_lshlrev_b32_e32 v222, 16, v135
	v_and_b32_e32 v223, 0xffff0000, v135
	v_pk_mul_f32 v[216:217], v[36:37], v[216:217] op_sel_hi:[0,1]
	v_pk_mul_f32 v[218:219], v[36:37], v[218:219] op_sel_hi:[0,1]
	v_pk_mul_f32 v[220:221], v[36:37], v[220:221] op_sel_hi:[0,1]
	v_pk_mul_f32 v[222:223], v[36:37], v[222:223] op_sel_hi:[0,1]
	v_pk_mul_f32 v[216:217], v[216:217], v[68:69]
	v_pk_mul_f32 v[218:219], v[218:219], v[70:71]
	v_pk_mul_f32 v[220:221], v[220:221], v[72:73]
	v_pk_mul_f32 v[222:223], v[222:223], v[74:75]
	global_store_dwordx4 v[32:33], v[216:219], off nt
	global_store_dwordx4 v[32:33], v[220:223], off offset:16 nt
	v_lshlrev_b32_e32 v224, 16, v136
	v_and_b32_e32 v225, 0xffff0000, v136
	v_lshlrev_b32_e32 v226, 16, v137
	v_and_b32_e32 v227, 0xffff0000, v137
	v_lshlrev_b32_e32 v228, 16, v138
	v_and_b32_e32 v229, 0xffff0000, v138
	v_lshlrev_b32_e32 v230, 16, v139
	v_and_b32_e32 v231, 0xffff0000, v139
	v_pk_mul_f32 v[224:225], v[36:37], v[224:225] op_sel_hi:[0,1]
	v_pk_mul_f32 v[226:227], v[36:37], v[226:227] op_sel_hi:[0,1]
	v_pk_mul_f32 v[228:229], v[36:37], v[228:229] op_sel_hi:[0,1]
	v_pk_mul_f32 v[230:231], v[36:37], v[230:231] op_sel_hi:[0,1]
	v_pk_mul_f32 v[224:225], v[224:225], v[76:77]
	v_pk_mul_f32 v[226:227], v[226:227], v[78:79]
	v_pk_mul_f32 v[228:229], v[228:229], v[80:81]
	v_pk_mul_f32 v[230:231], v[230:231], v[82:83]
; __device__ __forceinline__ void final_pass(const Params& p, int G) {
;     ...
;         for (int j = 0; j < 8; ++j) { const u32x4 w = hv[j]; const f32x4 g0 = gr[128 * j], g1 = gr[128 * j + 1];
;             const f32x4 v0 = (f32x4){__builtin_bit_cast(float, w.x << 16), __builtin_bit_cast(float, w.x & 0xffff0000u), __builtin_bit_cast(float, w.y << 16), __builtin_bit_cast(float, w.y & 0xffff0000u)};
;             const f32x4 v1 = (f32x4){__builtin_bit_cast(float, w.z << 16), __builtin_bit_cast(float, w.z & 0xffff0000u), __builtin_bit_cast(float, w.w << 16), __builtin_bit_cast(float, w.w & 0xffff0000u)};
;             __builtin_nontemporal_store(v0 * rstd * g0, xr + 128 * j); __builtin_nontemporal_store(v1 * rstd * g1, xr + 128 * j + 1); }
	global_store_dwordx4 v[32:33], v[224:227], off offset:2048 nt
	global_store_dwordx4 v[32:33], v[228:231], off offset:2064 nt
	v_lshlrev_b32_e32 v216, 16, v140
	v_and_b32_e32 v217, 0xffff0000, v140
	v_lshlrev_b32_e32 v218, 16, v141
	v_and_b32_e32 v219, 0xffff0000, v141
	v_lshlrev_b32_e32 v220, 16, v142
	v_and_b32_e32 v221, 0xffff0000, v142
	v_lshlrev_b32_e32 v222, 16, v143
	v_and_b32_e32 v223, 0xffff0000, v143
	v_pk_mul_f32 v[216:217], v[36:37], v[216:217] op_sel_hi:[0,1]
	v_pk_mul_f32 v[218:219], v[36:37], v[218:219] op_sel_hi:[0,1]
	v_pk_mul_f32 v[220:221], v[36:37], v[220:221] op_sel_hi:[0,1]
	v_pk_mul_f32 v[222:223], v[36:37], v[222:223] op_sel_hi:[0,1]
	v_pk_mul_f32 v[216:217], v[216:217], v[84:85]
	v_pk_mul_f32 v[218:219], v[218:219], v[86:87]
	v_pk_mul_f32 v[220:221], v[220:221], v[88:89]
	v_pk_mul_f32 v[222:223], v[222:223], v[90:91]
	global_store_dwordx4 v[38:39], v[216:219], off nt
	global_store_dwordx4 v[38:39], v[220:223], off offset:16 nt
	v_lshlrev_b32_e32 v224, 16, v144
	v_and_b32_e32 v225, 0xffff0000, v144
	v_lshlrev_b32_e32 v226, 16, v145
	v_and_b32_e32 v227, 0xffff0000, v145
	v_lshlrev_b32_e32 v228, 16, v146
	v_and_b32_e32 v229, 0xffff0000, v146
	v_lshlrev_b32_e32 v230, 16, v147
	v_and_b32_e32 v231, 0xffff0000, v147
	v_pk_mul_f32 v[224:225], v[36:37], v[224:225] op_sel_hi:[0,1]
	v_pk_mul_f32 v[226:227], v[36:37], v[226:227] op_sel_hi:[0,1]
	v_pk_mul_f32 v[228:229], v[36:37], v[228:229] op_sel_hi:[0,1]
	v_pk_mul_f32 v[230:231], v[36:37], v[230:231] op_sel_hi:[0,1]
	v_pk_mul_f32 v[224:225], v[224:225], v[92:93]
	v_pk_mul_f32 v[226:227], v[226:227], v[94:95]
	v_pk_mul_f32 v[228:229], v[228:229], v[96:97]
	v_pk_mul_f32 v[230:231], v[230:231], v[98:99]
	global_store_dwordx4 v[38:39], v[224:227], off offset:2048 nt
	global_store_dwordx4 v[38:39], v[228:231], off offset:2064 nt
	v_lshlrev_b32_e32 v216, 16, v148
	v_and_b32_e32 v217, 0xffff0000, v148
	v_lshlrev_b32_e32 v218, 16, v149
	v_and_b32_e32 v219, 0xffff0000, v149
	v_lshlrev_b32_e32 v220, 16, v150
	v_and_b32_e32 v221, 0xffff0000, v150
	v_lshlrev_b32_e32 v222, 16, v151
	v_and_b32_e32 v223, 0xffff0000, v151
	v_pk_mul_f32 v[216:217], v[36:37], v[216:217] op_sel_hi:[0,1]
	v_pk_mul_f32 v[218:219], v[36:37], v[218:219] op_sel_hi:[0,1]
	v_pk_mul_f32 v[220:221], v[36:37], v[220:221] op_sel_hi:[0,1]
	v_pk_mul_f32 v[222:223], v[36:37], v[222:223] op_sel_hi:[0,1]
	v_pk_mul_f32 v[216:217], v[216:217], v[100:101]
	v_pk_mul_f32 v[218:219], v[218:219], v[102:103]
	v_pk_mul_f32 v[220:221], v[220:221], v[104:105]
	v_pk_mul_f32 v[222:223], v[222:223], v[106:107]
	global_store_dwordx4 v[40:41], v[216:219], off nt
	global_store_dwordx4 v[40:41], v[220:223], off offset:16 nt
	v_lshlrev_b32_e32 v224, 16, v152
	v_and_b32_e32 v225, 0xffff0000, v152
	v_lshlrev_b32_e32 v226, 16, v153
	v_and_b32_e32 v227, 0xffff0000, v153
	v_lshlrev_b32_e32 v228, 16, v154
	v_and_b32_e32 v229, 0xffff0000, v154
	v_lshlrev_b32_e32 v230, 16, v155
	v_and_b32_e32 v231, 0xffff0000, v155
	v_pk_mul_f32 v[224:225], v[36:37], v[224:225] op_sel_hi:[0,1]
	v_pk_mul_f32 v[226:227], v[36:37], v[226:227] op_sel_hi:[0,1]
	v_pk_mul_f32 v[228:229], v[36:37], v[228:229] op_sel_hi:[0,1]
	v_pk_mul_f32 v[230:231], v[36:37], v[230:231] op_sel_hi:[0,1]
	v_pk_mul_f32 v[224:225], v[224:225], v[108:109]
	v_pk_mul_f32 v[226:227], v[226:227], v[110:111]
	v_pk_mul_f32 v[228:229], v[228:229], v[112:113]
	v_pk_mul_f32 v[230:231], v[230:231], v[114:115]
	global_store_dwordx4 v[40:41], v[224:227], off offset:2048 nt
	global_store_dwordx4 v[40:41], v[228:231], off offset:2064 nt
	v_lshlrev_b32_e32 v216, 16, v156
	v_and_b32_e32 v217, 0xffff0000, v156
	v_lshlrev_b32_e32 v218, 16, v157
	v_and_b32_e32 v219, 0xffff0000, v157
	v_lshlrev_b32_e32 v220, 16, v158
	v_and_b32_e32 v221, 0xffff0000, v158
	v_lshlrev_b32_e32 v222, 16, v159
	v_and_b32_e32 v223, 0xffff0000, v159
	v_pk_mul_f32 v[216:217], v[36:37], v[216:217] op_sel_hi:[0,1]
	v_pk_mul_f32 v[218:219], v[36:37], v[218:219] op_sel_hi:[0,1]
	v_pk_mul_f32 v[220:221], v[36:37], v[220:221] op_sel_hi:[0,1]
	v_pk_mul_f32 v[222:223], v[36:37], v[222:223] op_sel_hi:[0,1]
	v_pk_mul_f32 v[216:217], v[216:217], v[116:117]
	v_pk_mul_f32 v[218:219], v[218:219], v[118:119]
	v_pk_mul_f32 v[220:221], v[220:221], v[120:121]
	v_pk_mul_f32 v[222:223], v[222:223], v[122:123]
	global_store_dwordx4 v[42:43], v[216:219], off nt
	global_store_dwordx4 v[42:43], v[220:223], off offset:16 nt
	v_lshlrev_b32_e32 v224, 16, v160
	v_and_b32_e32 v225, 0xffff0000, v160
	v_lshlrev_b32_e32 v226, 16, v161
	v_and_b32_e32 v227, 0xffff0000, v161
	v_lshlrev_b32_e32 v228, 16, v162
	v_and_b32_e32 v229, 0xffff0000, v162
	v_lshlrev_b32_e32 v230, 16, v163
	v_and_b32_e32 v231, 0xffff0000, v163
	v_pk_mul_f32 v[224:225], v[36:37], v[224:225] op_sel_hi:[0,1]
	v_pk_mul_f32 v[226:227], v[36:37], v[226:227] op_sel_hi:[0,1]
	v_pk_mul_f32 v[228:229], v[36:37], v[228:229] op_sel_hi:[0,1]
	v_pk_mul_f32 v[230:231], v[36:37], v[230:231] op_sel_hi:[0,1]
	v_pk_mul_f32 v[224:225], v[224:225], v[124:125]
	v_pk_mul_f32 v[226:227], v[226:227], v[126:127]
	v_pk_mul_f32 v[228:229], v[228:229], v[128:129]
	v_pk_mul_f32 v[230:231], v[230:231], v[130:131]
	global_store_dwordx4 v[42:43], v[224:227], off offset:2048 nt
	global_store_dwordx4 v[42:43], v[228:231], off offset:2064 nt
	v_lshl_add_u64 v[32:33], v[32:33], 0, s[6:7]
	s_branch .LBB0_1055
; __device__ __forceinline__ void final_pass(const Params& p, int G) {
;     ...
;         for (int j = 0; j < 8; ++j) { const u32x4 w = hv[j]; const f32x4 g0 = gr[128 * j], g1 = gr[128 * j + 1];
;             const f32x4 v0 = (f32x4){__builtin_bit_cast(float, w.x << 16), __builtin_bit_cast(float, w.x & 0xffff0000u), __builtin_bit_cast(float, w.y << 16), __builtin_bit_cast(float, w.y & 0xffff0000u)};
;             const f32x4 v1 = (f32x4){__builtin_bit_cast(float, w.z << 16), __builtin_bit_cast(float, w.z & 0xffff0000u), __builtin_bit_cast(float, w.w << 16), __builtin_bit_cast(float, w.w & 0xffff0000u)};
;             __builtin_nontemporal_store(v0 * rstd * g0, xr + 128 * j); __builtin_nontemporal_store(v1 * rstd * g1, xr + 128 * j + 1); }
.Lfin_last_b:
	s_waitcnt vmcnt(0)
	v_fmamk_f32 v36, v197, 0x39800000, v13
	v_rsq_f32_e32 v36, v36
	v_lshl_add_u64 v[38:39], v[32:33], 0, s[16:17]
	v_lshl_add_u64 v[40:41], v[32:33], 0, s[18:19]
	v_lshl_add_u64 v[42:43], v[32:33], 0, s[20:21]
	v_lshlrev_b32_e32 v216, 16, v164
	v_and_b32_e32 v217, 0xffff0000, v164
	v_lshlrev_b32_e32 v218, 16, v165
	v_and_b32_e32 v219, 0xffff0000, v165
	v_lshlrev_b32_e32 v220, 16, v166
	v_and_b32_e32 v221, 0xffff0000, v166
	v_lshlrev_b32_e32 v222, 16, v167
	v_and_b32_e32 v223, 0xffff0000, v167
	v_pk_mul_f32 v[216:217], v[36:37], v[216:217] op_sel_hi:[0,1]
	v_pk_mul_f32 v[218:219], v[36:37], v[218:219] op_sel_hi:[0,1]
	v_pk_mul_f32 v[220:221], v[36:37], v[220:221] op_sel_hi:[0,1]
	v_pk_mul_f32 v[222:223], v[36:37], v[222:223] op_sel_hi:[0,1]
	v_pk_mul_f32 v[216:217], v[216:217], v[68:69]
	v_pk_mul_f32 v[218:219], v[218:219], v[70:71]
	v_pk_mul_f32 v[220:221], v[220:221], v[72:73]
	v_pk_mul_f32 v[222:223], v[222:223], v[74:75]
	global_store_dwordx4 v[32:33], v[216:219], off nt
	global_store_dwordx4 v[32:33], v[220:223], off offset:16 nt
	v_lshlrev_b32_e32 v224, 16, v168
	v_and_b32_e32 v225, 0xffff0000, v168
	v_lshlrev_b32_e32 v226, 16, v169
	v_and_b32_e32 v227, 0xffff0000, v169
	v_lshlrev_b32_e32 v228, 16, v170
	v_and_b32_e32 v229, 0xffff0000, v170
	v_lshlrev_b32_e32 v230, 16, v171
	v_and_b32_e32 v231, 0xffff0000, v171
	v_pk_mul_f32 v[224:225], v[36:37], v[224:225] op_sel_hi:[0,1]
	v_pk_mul_f32 v[226:227], v[36:37], v[226:227] op_sel_hi:[0,1]
	v_pk_mul_f32 v[228:229], v[36:37], v[228:229] op_sel_hi:[0,1]
	v_pk_mul_f32 v[230:231], v[36:37], v[230:231] op_sel_hi:[0,1]
	v_pk_mul_f32 v[224:225], v[224:225], v[76:77]
	v_pk_mul_f32 v[226:227], v[226:227], v[78:79]
	v_pk_mul_f32 v[228:229], v[228:229], v[80:81]
	v_pk_mul_f32 v[230:231], v[230:231], v[82:83]
	global_store_dwordx4 v[32:33], v[224:227], off offset:2048 nt
	global_store_dwordx4 v[32:33], v[228:231], off offset:2064 nt
	v_lshlrev_b32_e32 v216, 16, v172
	v_and_b32_e32 v217, 0xffff0000, v172
	v_lshlrev_b32_e32 v218, 16, v173
	v_and_b32_e32 v219, 0xffff0000, v173
	v_lshlrev_b32_e32 v220, 16, v174
	v_and_b32_e32 v221, 0xffff0000, v174
	v_lshlrev_b32_e32 v222, 16, v175
	v_and_b32_e32 v223, 0xffff0000, v175
	v_pk_mul_f32 v[216:217], v[36:37], v[216:217] op_sel_hi:[0,1]
	v_pk_mul_f32 v[218:219], v[36:37], v[218:219] op_sel_hi:[0,1]
	v_pk_mul_f32 v[220:221], v[36:37], v[220:221] op_sel_hi:[0,1]
	v_pk_mul_f32 v[222:223], v[36:37], v[222:223] op_sel_hi:[0,1]
	v_pk_mul_f32 v[216:217], v[216:217], v[84:85]
	v_pk_mul_f32 v[218:219], v[218:219], v[86:87]
	v_pk_mul_f32 v[220:221], v[220:221], v[88:89]
	v_pk_mul_f32 v[222:223], v[222:223], v[90:91]
	global_store_dwordx4 v[38:39], v[216:219], off nt
	global_store_dwordx4 v[38:39], v[220:223], off offset:16 nt
	v_lshlrev_b32_e32 v224, 16, v176
	v_and_b32_e32 v225, 0xffff0000, v176
	v_lshlrev_b32_e32 v226, 16, v177
	v_and_b32_e32 v227, 0xffff0000, v177
	v_lshlrev_b32_e32 v228, 16, v178
	v_and_b32_e32 v229, 0xffff0000, v178
	v_lshlrev_b32_e32 v230, 16, v179
	v_and_b32_e32 v231, 0xffff0000, v179
	v_pk_mul_f32 v[224:225], v[36:37], v[224:225] op_sel_hi:[0,1]
	v_pk_mul_f32 v[226:227], v[36:37], v[226:227] op_sel_hi:[0,1]
	v_pk_mul_f32 v[228:229], v[36:37], v[228:229] op_sel_hi:[0,1]
	v_pk_mul_f32 v[230:231], v[36:37], v[230:231] op_sel_hi:[0,1]
	v_pk_mul_f32 v[224:225], v[224:225], v[92:93]
	v_pk_mul_f32 v[226:227], v[226:227], v[94:95]
	v_pk_mul_f32 v[228:229], v[228:229], v[96:97]
	v_pk_mul_f32 v[230:231], v[230:231], v[98:99]
	global_store_dwordx4 v[38:39], v[224:227], off offset:2048 nt
; __device__ __forceinline__ void final_pass(const Params& p, int G) {
;     ...
;         for (int j = 0; j < 8; ++j) { const u32x4 w = hv[j]; const f32x4 g0 = gr[128 * j], g1 = gr[128 * j + 1];
;             const f32x4 v0 = (f32x4){__builtin_bit_cast(float, w.x << 16), __builtin_bit_cast(float, w.x & 0xffff0000u), __builtin_bit_cast(float, w.y << 16), __builtin_bit_cast(float, w.y & 0xffff0000u)};
;             const f32x4 v1 = (f32x4){__builtin_bit_cast(float, w.z << 16), __builtin_bit_cast(float, w.z & 0xffff0000u), __builtin_bit_cast(float, w.w << 16), __builtin_bit_cast(float, w.w & 0xffff0000u)};
;             __builtin_nontemporal_store(v0 * rstd * g0, xr + 128 * j); __builtin_nontemporal_store(v1 * rstd * g1, xr + 128 * j + 1); }
	global_store_dwordx4 v[38:39], v[228:231], off offset:2064 nt
	v_lshlrev_b32_e32 v216, 16, v180
	v_and_b32_e32 v217, 0xffff0000, v180
	v_lshlrev_b32_e32 v218, 16, v181
	v_and_b32_e32 v219, 0xffff0000, v181
	v_lshlrev_b32_e32 v220, 16, v182
	v_and_b32_e32 v221, 0xffff0000, v182
	v_lshlrev_b32_e32 v222, 16, v183
	v_and_b32_e32 v223, 0xffff0000, v183
	v_pk_mul_f32 v[216:217], v[36:37], v[216:217] op_sel_hi:[0,1]
	v_pk_mul_f32 v[218:219], v[36:37], v[218:219] op_sel_hi:[0,1]
	v_pk_mul_f32 v[220:221], v[36:37], v[220:221] op_sel_hi:[0,1]
	v_pk_mul_f32 v[222:223], v[36:37], v[222:223] op_sel_hi:[0,1]
	v_pk_mul_f32 v[216:217], v[216:217], v[100:101]
	v_pk_mul_f32 v[218:219], v[218:219], v[102:103]
	v_pk_mul_f32 v[220:221], v[220:221], v[104:105]
	v_pk_mul_f32 v[222:223], v[222:223], v[106:107]
	global_store_dwordx4 v[40:41], v[216:219], off nt
	global_store_dwordx4 v[40:41], v[220:223], off offset:16 nt
	v_lshlrev_b32_e32 v224, 16, v184
	v_and_b32_e32 v225, 0xffff0000, v184
	v_lshlrev_b32_e32 v226, 16, v185
	v_and_b32_e32 v227, 0xffff0000, v185
	v_lshlrev_b32_e32 v228, 16, v186
	v_and_b32_e32 v229, 0xffff0000, v186
	v_lshlrev_b32_e32 v230, 16, v187
	v_and_b32_e32 v231, 0xffff0000, v187
	v_pk_mul_f32 v[224:225], v[36:37], v[224:225] op_sel_hi:[0,1]
	v_pk_mul_f32 v[226:227], v[36:37], v[226:227] op_sel_hi:[0,1]
	v_pk_mul_f32 v[228:229], v[36:37], v[228:229] op_sel_hi:[0,1]
	v_pk_mul_f32 v[230:231], v[36:37], v[230:231] op_sel_hi:[0,1]
	v_pk_mul_f32 v[224:225], v[224:225], v[108:109]
	v_pk_mul_f32 v[226:227], v[226:227], v[110:111]
	v_pk_mul_f32 v[228:229], v[228:229], v[112:113]
	v_pk_mul_f32 v[230:231], v[230:231], v[114:115]
	global_store_dwordx4 v[40:41], v[224:227], off offset:2048 nt
	global_store_dwordx4 v[40:41], v[228:231], off offset:2064 nt
	v_lshlrev_b32_e32 v216, 16, v188
	v_and_b32_e32 v217, 0xffff0000, v188
	v_lshlrev_b32_e32 v218, 16, v189
	v_and_b32_e32 v219, 0xffff0000, v189
	v_lshlrev_b32_e32 v220, 16, v190
	v_and_b32_e32 v221, 0xffff0000, v190
	v_lshlrev_b32_e32 v222, 16, v191
	v_and_b32_e32 v223, 0xffff0000, v191
	v_pk_mul_f32 v[216:217], v[36:37], v[216:217] op_sel_hi:[0,1]
	v_pk_mul_f32 v[218:219], v[36:37], v[218:219] op_sel_hi:[0,1]
	v_pk_mul_f32 v[220:221], v[36:37], v[220:221] op_sel_hi:[0,1]
	v_pk_mul_f32 v[222:223], v[36:37], v[222:223] op_sel_hi:[0,1]
	v_pk_mul_f32 v[216:217], v[216:217], v[116:117]
	v_pk_mul_f32 v[218:219], v[218:219], v[118:119]
	v_pk_mul_f32 v[220:221], v[220:221], v[120:121]
	v_pk_mul_f32 v[222:223], v[222:223], v[122:123]
	global_store_dwordx4 v[42:43], v[216:219], off nt
	global_store_dwordx4 v[42:43], v[220:223], off offset:16 nt
	v_lshlrev_b32_e32 v224, 16, v192
	v_and_b32_e32 v225, 0xffff0000, v192
	v_lshlrev_b32_e32 v226, 16, v193
	v_and_b32_e32 v227, 0xffff0000, v193
	v_lshlrev_b32_e32 v228, 16, v194
	v_and_b32_e32 v229, 0xffff0000, v194
	v_lshlrev_b32_e32 v230, 16, v195
	v_and_b32_e32 v231, 0xffff0000, v195
	v_pk_mul_f32 v[224:225], v[36:37], v[224:225] op_sel_hi:[0,1]
	v_pk_mul_f32 v[226:227], v[36:37], v[226:227] op_sel_hi:[0,1]
	v_pk_mul_f32 v[228:229], v[36:37], v[228:229] op_sel_hi:[0,1]
	v_pk_mul_f32 v[230:231], v[36:37], v[230:231] op_sel_hi:[0,1]
	v_pk_mul_f32 v[224:225], v[224:225], v[124:125]
	v_pk_mul_f32 v[226:227], v[226:227], v[126:127]
	v_pk_mul_f32 v[228:229], v[228:229], v[128:129]
	v_pk_mul_f32 v[230:231], v[230:231], v[130:131]
	global_store_dwordx4 v[42:43], v[224:227], off offset:2048 nt
	global_store_dwordx4 v[42:43], v[228:231], off offset:2064 nt
	v_lshl_add_u64 v[32:33], v[32:33], 0, s[6:7]
